# o27 + w2d weight conversion (352 filler pulls) moved out of the filler queue into GU2's idle last-round workgroups (same wave queue as w1d in GU1)
# speedup vs baseline: 1.0258x; 1.0073x over previous
.LBB0_1229:
	s_or_b64 exec, exec, s[0:1]
	s_waitcnt lgkmcnt(0)
	s_barrier
	ds_read_b32 v1, v155
	s_movk_i32 s0, 0x74f
	s_waitcnt lgkmcnt(0)
	v_add_u32_e32 v1, s98, v1
	v_cmp_lt_u32_e32 vcc, s0, v1
	v_readfirstlane_b32 s42, v1
	s_mov_b64 s[0:1], -1
	s_cbranch_vccnz .LBB0_1224
	s_cmpk_gt_u32 s42, 0x2ff
	s_cbranch_scc1 .Lq_nomap
	s_cmpk_lt_u32 s42, 0x80
	s_cbranch_scc1 .Lq_nomap
	s_cmpk_lt_u32 s42, 0x280
	s_cbranch_scc1 .Lq_g1
	s_sub_u32 s42, s42, 0x200
	s_branch .Lq_nomap

.Lfill_go:
	v_lshl_add_u32 v1, s42, 3, v131
	s_movk_i32 s0, 0x1600
	v_mov_b32_e32 v224, 0xb00
	v_cmp_le_i32_e32 vcc, s0, v1
	s_nop 1
	v_cndmask_b32_e32 v224, 0, v224, vcc
	v_add_u32_e32 v1, v1, v224
	s_movk_i32 s0, 0x2500
	v_cmp_gt_i32_e32 vcc, s0, v1
	s_and_saveexec_b64 s[0:1], vcc
	s_xor_b64 s[2:3], exec, s[0:1]
	s_cbranch_execz .LBB0_1270
	s_movk_i32 s0, 0x2100
	v_lshlrev_b32_e32 v2, 6, v1
	v_cmp_gt_i32_e32 vcc, s0, v1
	s_and_saveexec_b64 s[0:1], vcc
	s_xor_b64 s[4:5], exec, s[0:1]
	s_cbranch_execz .LBB0_1267
	s_movk_i32 s0, 0x15ff
	v_cmp_lt_i32_e32 vcc, s0, v1
	s_and_saveexec_b64 s[0:1], vcc
	s_xor_b64 s[0:1], exec, s[0:1]
	s_cbranch_execz .LBB0_1238
	v_lshlrev_b32_e32 v1, 1, v1
	v_and_b32_e32 v1, 0x7fffffc0, v1
	v_add_u32_e32 v66, 0xffffd400, v1
	v_or_b32_e32 v134, v66, v132
	v_readlane_b32 s8, v253, 40
	v_and_b32_e32 v68, 0x7c0, v2
	v_lshlrev_b64 v[2:3], 13, v[134:135]
	v_readlane_b32 s22, v253, 54
	v_readlane_b32 s23, v253, 55
	v_lshlrev_b32_e32 v134, 2, v68
	v_mov_b32_e32 v145, v135
	v_lshl_add_u64 v[2:3], s[22:23], 0, v[2:3]
	v_lshl_add_u64 v[2:3], v[2:3], 0, v[134:135]
	s_waitcnt vmcnt(9)
	v_lshl_add_u64 v[58:59], v[2:3], 0, v[144:145]
	s_movk_i32 s8, 0x2000
	v_add_co_u32_e32 v6, vcc, s8, v58
	s_movk_i32 s6, 0x4000
	s_nop 0
	v_addc_co_u32_e32 v7, vcc, 0, v59, vcc
	v_add_co_u32_e32 v10, vcc, s6, v58
	s_movk_i32 s6, 0x6000
	s_nop 0
	v_addc_co_u32_e32 v11, vcc, 0, v59, vcc
	v_add_co_u32_e32 v14, vcc, s6, v58
	s_mov_b32 s6, 0x8000
	s_nop 0
	v_addc_co_u32_e32 v15, vcc, 0, v59, vcc
	v_add_co_u32_e32 v18, vcc, s6, v58
	s_mov_b32 s6, 0xa000
	s_nop 0
	v_addc_co_u32_e32 v19, vcc, 0, v59, vcc
	v_add_co_u32_e32 v22, vcc, s6, v58
	s_mov_b32 s6, 0xc000
	s_nop 0
	v_addc_co_u32_e32 v23, vcc, 0, v59, vcc
	v_add_co_u32_e32 v26, vcc, s6, v58
	s_mov_b32 s6, 0xe000
	s_nop 0
	v_addc_co_u32_e32 v27, vcc, 0, v59, vcc
	v_add_co_u32_e32 v30, vcc, s6, v58
	s_mov_b32 s6, 0x10000
	s_nop 0
	v_addc_co_u32_e32 v31, vcc, 0, v59, vcc
	v_add_co_u32_e32 v34, vcc, s6, v58
	s_mov_b32 s6, 0x12000
	s_nop 0
	v_addc_co_u32_e32 v35, vcc, 0, v59, vcc
	v_add_co_u32_e32 v38, vcc, s6, v58
	s_mov_b32 s6, 0x14000
	s_nop 0
	v_addc_co_u32_e32 v39, vcc, 0, v59, vcc
	v_add_co_u32_e32 v42, vcc, s6, v58
	s_mov_b32 s6, 0x16000
	s_nop 0
	v_addc_co_u32_e32 v43, vcc, 0, v59, vcc
	v_add_co_u32_e32 v46, vcc, s6, v58
	s_mov_b32 s6, 0x18000
	s_nop 0
	v_addc_co_u32_e32 v47, vcc, 0, v59, vcc
	v_add_co_u32_e32 v50, vcc, s6, v58
	s_mov_b32 s6, 0x1a000
	s_nop 0
	v_addc_co_u32_e32 v51, vcc, 0, v59, vcc
	v_add_co_u32_e32 v54, vcc, s6, v58
	s_mov_b32 s6, 0x1c000
	s_nop 0
	v_addc_co_u32_e32 v55, vcc, 0, v59, vcc
	v_add_co_u32_e32 v60, vcc, s6, v58
	s_mov_b32 s6, 0x1e000
	s_nop 0
	v_addc_co_u32_e32 v61, vcc, 0, v59, vcc
	s_waitcnt vmcnt(8)
	v_add_co_u32_e32 v62, vcc, s6, v58
	global_load_dwordx4 v[2:5], v[58:59], off nt
	s_nop 0
	global_load_dwordx4 v[6:9], v[6:7], off nt
	s_nop 0
	global_load_dwordx4 v[10:13], v[10:11], off nt
	s_nop 0
	global_load_dwordx4 v[14:17], v[14:15], off nt
	s_nop 0
	global_load_dwordx4 v[18:21], v[18:19], off nt
	s_nop 0
	global_load_dwordx4 v[22:25], v[22:23], off nt
	s_nop 0
	global_load_dwordx4 v[26:29], v[26:27], off nt
	s_nop 0
	global_load_dwordx4 v[30:33], v[30:31], off nt
	v_addc_co_u32_e32 v63, vcc, 0, v59, vcc
	global_load_dwordx4 v[34:37], v[34:35], off nt
	s_nop 0
	global_load_dwordx4 v[38:41], v[38:39], off nt
	s_nop 0
	global_load_dwordx4 v[42:45], v[42:43], off nt
	s_nop 0
	global_load_dwordx4 v[46:49], v[46:47], off nt
	s_nop 0
	global_load_dwordx4 v[50:53], v[50:51], off nt
	s_nop 0
	global_load_dwordx4 v[54:57], v[54:55], off nt
	s_nop 0
	global_load_dwordx4 v[58:61], v[60:61], off nt
	s_nop 0
	global_load_dwordx4 v[62:65], v[62:63], off nt
	v_or_b32_e32 v1, v68, v130
	v_mul_u32_u24_e32 v1, 0x1600, v1
	v_readlane_b32 s6, v254, 30
	v_lshlrev_b32_e32 v134, 1, v1
	v_readlane_b32 s7, v254, 31
	v_mov_b32_e32 v67, v135
	v_mov_b32_e32 v147, v135
	v_lshl_add_u64 v[68:69], s[6:7], 0, v[134:135]
	v_lshl_add_u64 v[66:67], v[66:67], 1, v[68:69]
	v_lshl_add_u64 v[74:75], v[66:67], 0, v[146:147]
	s_movk_i32 s6, 0x5000
	v_readlane_b32 s9, v253, 41
	v_readlane_b32 s10, v253, 42
	v_readlane_b32 s11, v253, 43
	v_readlane_b32 s12, v253, 44
	v_readlane_b32 s13, v253, 45
	v_readlane_b32 s14, v253, 46
	v_readlane_b32 s15, v253, 47
	v_readlane_b32 s16, v253, 48
	v_readlane_b32 s17, v253, 49
	v_readlane_b32 s18, v253, 50
	v_readlane_b32 s19, v253, 51
	v_readlane_b32 s20, v253, 52
	v_readlane_b32 s21, v253, 53
	s_waitcnt vmcnt(14)
	v_cvt_pk_bf16_f32 v66, v2, v6
	s_waitcnt vmcnt(12)
	v_cvt_pk_bf16_f32 v67, v10, v14
	s_waitcnt vmcnt(10)
	v_cvt_pk_bf16_f32 v68, v18, v22
	s_waitcnt vmcnt(8)
	v_cvt_pk_bf16_f32 v69, v26, v30
	v_add_co_u32_e32 v2, vcc, s8, v74
	s_waitcnt vmcnt(6)
	v_cvt_pk_bf16_f32 v70, v34, v38
	s_waitcnt vmcnt(4)
	v_cvt_pk_bf16_f32 v71, v42, v46
	s_waitcnt vmcnt(2)
	v_cvt_pk_bf16_f32 v72, v50, v54
	s_waitcnt vmcnt(0)
	v_cvt_pk_bf16_f32 v73, v58, v62
	global_store_dwordx4 v[74:75], v[66:69], off
	global_store_dwordx4 v[74:75], v[70:73], off offset:16
	v_cvt_pk_bf16_f32 v6, v37, v41
	v_cvt_pk_bf16_f32 v66, v3, v7
	v_cvt_pk_bf16_f32 v67, v11, v15
	v_cvt_pk_bf16_f32 v68, v19, v23
	v_cvt_pk_bf16_f32 v69, v27, v31
	v_addc_co_u32_e32 v3, vcc, 0, v75, vcc
	v_cvt_pk_bf16_f32 v70, v35, v39
	v_cvt_pk_bf16_f32 v71, v43, v47
	v_cvt_pk_bf16_f32 v72, v51, v55
	v_cvt_pk_bf16_f32 v73, v59, v63
	global_store_dwordx4 v[2:3], v[66:69], off offset:3072
	global_store_dwordx4 v[2:3], v[70:73], off offset:3088
	v_add_co_u32_e32 v2, vcc, s6, v74
	v_cvt_pk_bf16_f32 v66, v4, v8
	s_nop 0
	v_addc_co_u32_e32 v3, vcc, 0, v75, vcc
	v_cvt_pk_bf16_f32 v67, v12, v16
	v_cvt_pk_bf16_f32 v68, v20, v24
	v_cvt_pk_bf16_f32 v69, v28, v32
	v_add_co_u32_e32 v10, vcc, 0x8000, v74
	v_cvt_pk_bf16_f32 v70, v36, v40
	v_cvt_pk_bf16_f32 v71, v44, v48
	v_cvt_pk_bf16_f32 v72, v52, v56
	v_cvt_pk_bf16_f32 v73, v60, v64
	global_store_dwordx4 v[2:3], v[66:69], off offset:2048
	global_store_dwordx4 v[2:3], v[70:73], off offset:2064
	v_cvt_pk_bf16_f32 v2, v5, v9
	v_cvt_pk_bf16_f32 v3, v13, v17
	v_cvt_pk_bf16_f32 v4, v21, v25
	v_cvt_pk_bf16_f32 v5, v29, v33
	v_addc_co_u32_e32 v11, vcc, 0, v75, vcc
	v_cvt_pk_bf16_f32 v7, v45, v49
	v_cvt_pk_bf16_f32 v8, v53, v57
	v_cvt_pk_bf16_f32 v9, v61, v65
	global_store_dwordx4 v[10:11], v[2:5], off offset:1024
	global_store_dwordx4 v[10:11], v[6:9], off offset:1040

.LBB0_2074:
	s_waitcnt vmcnt(0)
	s_mov_b32 s28, s56
	s_barrier
.LBB0_2075:
	s_mov_b64 exec, -1
	v_readlane_b32 s98, v253, 0
	v_readlane_b32 s99, v253, 23
	s_nop 3
	s_cmpk_lg_u32 s99, 0x100
	s_cbranch_scc1 .Lw2d_go
	s_cmpk_lt_u32 s98, 0xac
	s_cbranch_scc1 .Lw2d_done
.Lw2d_go:
	v_readlane_b32 s0, v253, 21
	v_readlane_b32 s1, v253, 22
	s_nop 3
	s_sub_u32 s0, s0, 0xe0
	s_subb_u32 s1, s1, 0
	s_load_dwordx2 s[10:11], s[0:1], 0xb8
	s_add_u32 s8, s86, 0xc900
	s_addc_u32 s9, s87, 0
	v_and_b32_e32 v6, 15, v0
	v_and_b32_e32 v7, 48, v0
	v_lshlrev_b32_e32 v8, 13, v7
	v_lshl_or_b32 v8, v6, 4, v8
	v_lshlrev_b32_e32 v9, 2, v6
	v_mul_u32_u24_e32 v9, 0x2c00, v9
	v_lshl_add_u32 v12, v7, 1, v9
	v_add_u32_e32 v13, 0x2c00, v12
	v_add_u32_e32 v14, 0x5800, v12
	v_add_u32_e32 v15, 0x8400, v12
	v_mov_b32_e32 v16, 0
	v_mov_b32_e32 v17, 1
	s_mov_b64 exec, 1
	global_atomic_add v18, v16, v17, s[8:9] sc0
	s_mov_b64 exec, -1
	s_waitcnt vmcnt(0) lgkmcnt(0)
.Lw2d_loop:
	v_readfirstlane_b32 s98, v18
	s_nop 3
	s_cmpk_ge_u32 s98, 0x580
	s_cbranch_scc1 .Lw2d_done
	s_lshr_b32 s99, s98, 4
	s_and_b32 s100, s98, 15
	s_lshl_b32 s101, s99, 19
	s_lshl_b32 s0, s100, 9
	s_add_u32 s0, s0, s101
	s_add_u32 s0, s10, s0
	s_addc_u32 s1, s11, 0
	s_mul_i32 s2, s100, 0x160000
	s_lshl_b32 s3, s99, 7
	s_add_u32 s2, s2, s3
	s_add_u32 s2, s2, 0xb860200
	s_add_u32 s2, s86, s2
	s_addc_u32 s3, s87, 0
	s_add_u32 s6, s2, 0xb0000
	s_addc_u32 s7, s3, 0
	global_load_dwordx4 v[154:157], v8, s[0:1] nt
	global_load_dwordx4 v[204:207], v8, s[0:1] offset:256 nt
	s_add_u32 s0, s0, 0x2000
	s_addc_u32 s1, s1, 0
	global_load_dwordx4 v[158:161], v8, s[0:1] nt
	global_load_dwordx4 v[208:211], v8, s[0:1] offset:256 nt
	s_add_u32 s0, s0, 0x2000
	s_addc_u32 s1, s1, 0
	global_load_dwordx4 v[162:165], v8, s[0:1] nt
	global_load_dwordx4 v[212:215], v8, s[0:1] offset:256 nt
	s_add_u32 s0, s0, 0x2000
	s_addc_u32 s1, s1, 0
	global_load_dwordx4 v[166:169], v8, s[0:1] nt
	global_load_dwordx4 v[216:219], v8, s[0:1] offset:256 nt
	s_add_u32 s0, s0, 0x2000
	s_addc_u32 s1, s1, 0
	global_load_dwordx4 v[170:173], v8, s[0:1] nt
	global_load_dwordx4 v[220:223], v8, s[0:1] offset:256 nt
	s_add_u32 s0, s0, 0x2000
	s_addc_u32 s1, s1, 0
	global_load_dwordx4 v[174:177], v8, s[0:1] nt
	global_load_dwordx4 v[224:227], v8, s[0:1] offset:256 nt
	s_add_u32 s0, s0, 0x2000
	s_addc_u32 s1, s1, 0
	global_load_dwordx4 v[178:181], v8, s[0:1] nt
	global_load_dwordx4 v[228:231], v8, s[0:1] offset:256 nt
	s_add_u32 s0, s0, 0x2000
	s_addc_u32 s1, s1, 0
	global_load_dwordx4 v[182:185], v8, s[0:1] nt
	global_load_dwordx4 v[232:235], v8, s[0:1] offset:256 nt
	s_add_u32 s0, s0, 0x2000
	s_addc_u32 s1, s1, 0
	global_load_dwordx4 v[186:189], v8, s[0:1] nt
	global_load_dwordx4 v[236:239], v8, s[0:1] offset:256 nt
	s_add_u32 s0, s0, 0x2000
	s_addc_u32 s1, s1, 0
	global_load_dwordx4 v[190:193], v8, s[0:1] nt
	global_load_dwordx4 v[240:243], v8, s[0:1] offset:256 nt
	s_add_u32 s0, s0, 0x2000
	s_addc_u32 s1, s1, 0
	global_load_dwordx4 v[194:197], v8, s[0:1] nt
	global_load_dwordx4 v[244:247], v8, s[0:1] offset:256 nt
	s_add_u32 s0, s0, 0x2000
	s_addc_u32 s1, s1, 0
	global_load_dwordx4 v[198:201], v8, s[0:1] nt
	global_load_dwordx4 v[248:251], v8, s[0:1] offset:256 nt
	s_add_u32 s0, s0, 0x2000
	s_addc_u32 s1, s1, 0
	global_load_dwordx4 v[130:133], v8, s[0:1] nt
	global_load_dwordx4 v[50:53], v8, s[0:1] offset:256 nt
	s_add_u32 s0, s0, 0x2000
	s_addc_u32 s1, s1, 0
	global_load_dwordx4 v[134:137], v8, s[0:1] nt
	global_load_dwordx4 v[54:57], v8, s[0:1] offset:256 nt
	s_add_u32 s0, s0, 0x2000
	s_addc_u32 s1, s1, 0
	global_load_dwordx4 v[138:141], v8, s[0:1] nt
	global_load_dwordx4 v[58:61], v8, s[0:1] offset:256 nt
	s_add_u32 s0, s0, 0x2000
	s_addc_u32 s1, s1, 0
	global_load_dwordx4 v[142:145], v8, s[0:1] nt
	global_load_dwordx4 v[62:65], v8, s[0:1] offset:256 nt
	s_mov_b64 exec, 1
	global_atomic_add v18, v16, v17, s[8:9] sc0
	s_mov_b64 exec, -1
	s_waitcnt vmcnt(1)
	v_cvt_pk_bf16_f32 v20, v154, v158
	v_cvt_pk_bf16_f32 v21, v162, v166
	v_cvt_pk_bf16_f32 v22, v170, v174
	v_cvt_pk_bf16_f32 v23, v178, v182
	global_store_dwordx4 v12, v[20:23], s[2:3]
	v_cvt_pk_bf16_f32 v24, v186, v190
	v_cvt_pk_bf16_f32 v25, v194, v198
	v_cvt_pk_bf16_f32 v26, v130, v134
	v_cvt_pk_bf16_f32 v27, v138, v142
	global_store_dwordx4 v12, v[24:27], s[2:3] offset:16
	v_cvt_pk_bf16_f32 v28, v155, v159
	v_cvt_pk_bf16_f32 v29, v163, v167
	v_cvt_pk_bf16_f32 v30, v171, v175
	v_cvt_pk_bf16_f32 v31, v179, v183
	global_store_dwordx4 v13, v[28:31], s[2:3]
	v_cvt_pk_bf16_f32 v32, v187, v191
	v_cvt_pk_bf16_f32 v33, v195, v199
	v_cvt_pk_bf16_f32 v34, v131, v135
	v_cvt_pk_bf16_f32 v35, v139, v143
	global_store_dwordx4 v13, v[32:35], s[2:3] offset:16
	v_cvt_pk_bf16_f32 v36, v156, v160
	v_cvt_pk_bf16_f32 v37, v164, v168
	v_cvt_pk_bf16_f32 v38, v172, v176
	v_cvt_pk_bf16_f32 v39, v180, v184
	global_store_dwordx4 v14, v[36:39], s[2:3]
	v_cvt_pk_bf16_f32 v40, v188, v192
	v_cvt_pk_bf16_f32 v41, v196, v200
	v_cvt_pk_bf16_f32 v42, v132, v136
	v_cvt_pk_bf16_f32 v43, v140, v144
	global_store_dwordx4 v14, v[40:43], s[2:3] offset:16
	v_cvt_pk_bf16_f32 v20, v157, v161
	v_cvt_pk_bf16_f32 v21, v165, v169
	v_cvt_pk_bf16_f32 v22, v173, v177
	v_cvt_pk_bf16_f32 v23, v181, v185
	global_store_dwordx4 v15, v[20:23], s[2:3]
	v_cvt_pk_bf16_f32 v24, v189, v193
	v_cvt_pk_bf16_f32 v25, v197, v201
	v_cvt_pk_bf16_f32 v26, v133, v137
	v_cvt_pk_bf16_f32 v27, v141, v145
	global_store_dwordx4 v15, v[24:27], s[2:3] offset:16
	v_cvt_pk_bf16_f32 v28, v204, v208
	v_cvt_pk_bf16_f32 v29, v212, v216
	v_cvt_pk_bf16_f32 v30, v220, v224
	v_cvt_pk_bf16_f32 v31, v228, v232
	global_store_dwordx4 v12, v[28:31], s[6:7]
	v_cvt_pk_bf16_f32 v32, v236, v240
	v_cvt_pk_bf16_f32 v33, v244, v248
	v_cvt_pk_bf16_f32 v34, v50, v54
	v_cvt_pk_bf16_f32 v35, v58, v62
	global_store_dwordx4 v12, v[32:35], s[6:7] offset:16
	v_cvt_pk_bf16_f32 v36, v205, v209
	v_cvt_pk_bf16_f32 v37, v213, v217
	v_cvt_pk_bf16_f32 v38, v221, v225
	v_cvt_pk_bf16_f32 v39, v229, v233
	global_store_dwordx4 v13, v[36:39], s[6:7]
	v_cvt_pk_bf16_f32 v40, v237, v241
	v_cvt_pk_bf16_f32 v41, v245, v249
	v_cvt_pk_bf16_f32 v42, v51, v55
	v_cvt_pk_bf16_f32 v43, v59, v63
	global_store_dwordx4 v13, v[40:43], s[6:7] offset:16
	v_cvt_pk_bf16_f32 v20, v206, v210
	v_cvt_pk_bf16_f32 v21, v214, v218
	v_cvt_pk_bf16_f32 v22, v222, v226
	v_cvt_pk_bf16_f32 v23, v230, v234
	global_store_dwordx4 v14, v[20:23], s[6:7]
	v_cvt_pk_bf16_f32 v24, v238, v242
	v_cvt_pk_bf16_f32 v25, v246, v250
	v_cvt_pk_bf16_f32 v26, v52, v56
	v_cvt_pk_bf16_f32 v27, v60, v64
	global_store_dwordx4 v14, v[24:27], s[6:7] offset:16
	v_cvt_pk_bf16_f32 v28, v207, v211
	v_cvt_pk_bf16_f32 v29, v215, v219
	v_cvt_pk_bf16_f32 v30, v223, v227
	v_cvt_pk_bf16_f32 v31, v231, v235
	global_store_dwordx4 v15, v[28:31], s[6:7]
	v_cvt_pk_bf16_f32 v32, v239, v243
	v_cvt_pk_bf16_f32 v33, v247, v251
	v_cvt_pk_bf16_f32 v34, v53, v57
	v_cvt_pk_bf16_f32 v35, v61, v65
	global_store_dwordx4 v15, v[32:35], s[6:7] offset:16
	s_waitcnt vmcnt(16)
	s_branch .Lw2d_loop
